# waves 0-3 raise priority already at the kk epilogue (their chain gates the step-4 barrier); waves 4-7 have slack there after the half move
# baseline (speedup 1.0000x reference)
.LBB0_135:
	s_setprio 2
	s_and_b64 vcc, exec, s[28:29]
	v_lshl_or_b32 v96, s52, 5, v94
	s_cbranch_vccnz .LBB0_170
	s_branch .LBB0_203
